# norm2 tiles: all 20 loads of a row pair issued up front (was waiting after every 2-3 loads)
# speedup vs baseline: 1.0252x; 1.0044x over previous
.LBB0_1242:
	v_mov_b32_e32 v0, v133
	v_mov_b32_e32 v4, s95
	v_ashrrev_i32_e32 v2, 5, v0
	v_and_b32_e32 v2, -2, v2
	v_add_u32_e32 v18, s3, v2
	v_cmp_gt_i32_e32 vcc, s36, v18
	v_add_u32_e32 v2, 0xffffc000, v18
	v_ashrrev_i32_e32 v19, 31, v18
	v_mov_b32_e32 v5, s89
	v_and_b32_e32 v68, 63, v0
	v_min_i32_e32 v0, 0x4000, v18
	v_cndmask_b32_e32 v3, 0, v19, vcc
	v_cndmask_b32_e32 v2, v2, v18, vcc
	v_cndmask_b32_e32 v5, v4, v5, vcc
	v_mov_b32_e32 v4, s94
	v_mov_b32_e32 v6, s88
	v_ashrrev_i32_e32 v0, 12, v0
	v_cndmask_b32_e32 v4, v4, v6, vcc
	v_lshlrev_b64 v[2:3], 12, v[2:3]
	v_add_u32_e32 v0, s7, v0
	v_mov_b64_e32 v[6:7], s[90:91]
	v_lshl_add_u64 v[2:3], v[4:5], 0, v[2:3]
	v_mad_i64_i32 v[6:7], s[0:1], v0, s33, v[6:7]
	v_lshlrev_b32_e32 v0, 4, v68
	v_lshl_add_u64 v[4:5], v[2:3], 0, s[8:9]
	s_mov_b64 s[0:1], 0x3000
	v_lshl_add_u64 v[20:21], v[2:3], 0, v[0:1]
	v_or_b32_e32 v2, 0x400, v0
	v_mov_b32_e32 v3, v1
	v_or_b32_e32 v10, 0x800, v0
	v_mov_b32_e32 v11, v1
	v_or_b32_e32 v12, 0xc00, v0
	v_mov_b32_e32 v13, v1
	v_lshl_add_u64 v[8:9], v[6:7], 0, s[0:1]
	v_lshl_add_u64 v[46:47], v[4:5], 0, v[0:1]
	v_lshl_add_u64 v[48:49], v[4:5], 0, v[2:3]
	v_lshl_add_u64 v[14:15], v[4:5], 0, v[10:11]
	v_lshl_add_u64 v[22:23], v[4:5], 0, v[12:13]
	v_lshl_add_u64 v[4:5], v[6:7], 0, s[38:39]
	v_lshl_add_u64 v[50:51], v[4:5], 0, v[0:1]
	v_lshl_add_u64 v[42:43], v[8:9], 0, v[2:3]
	v_lshl_add_u64 v[44:45], v[4:5], 0, v[2:3]
	v_lshl_add_u64 v[38:39], v[8:9], 0, v[10:11]
	v_lshl_add_u64 v[40:41], v[4:5], 0, v[10:11]
	v_lshl_add_u64 v[34:35], v[8:9], 0, v[12:13]
	v_lshl_add_u64 v[36:37], v[4:5], 0, v[12:13]
	v_lshl_add_u64 v[26:27], v[8:9], 0, v[0:1]
	v_lshlrev_b64 v[18:19], 11, v[18:19]
	v_lshl_add_u64 v[56:57], s[46:47], 0, v[18:19]
	v_lshlrev_b32_e32 v60, 3, v68
	v_mov_b32_e32 v61, v1
	v_lshl_add_u64 v[56:57], v[56:57], 0, v[60:61]
	s_add_i32 s4, s4, s66
	s_add_i32 s3, s3, s41
	global_load_dwordx4 v[72:75], v[20:21], off
	global_load_dwordx4 v[76:79], v[20:21], off offset:1024
	global_load_dwordx4 v[80:83], v[20:21], off offset:2048
	global_load_dwordx4 v[84:87], v[20:21], off offset:3072
	global_load_dwordx4 v[88:91], v[46:47], off
	global_load_dwordx4 v[92:95], v[48:49], off
	global_load_dwordx4 v[96:99], v[14:15], off
	global_load_dwordx4 v[100:103], v[22:23], off
	global_load_dwordx4 v[136:139], v0, s[34:35]
	global_load_dwordx4 v[140:143], v0, s[34:35] offset:1024
	global_load_dwordx4 v[144:147], v0, s[34:35] offset:2048
	global_load_dwordx4 v[148:151], v0, s[34:35] offset:3072
	global_load_dwordx4 v[152:155], v[26:27], off
	global_load_dwordx4 v[156:159], v[42:43], off
	global_load_dwordx4 v[160:163], v[38:39], off
	global_load_dwordx4 v[164:167], v[34:35], off
	global_load_dwordx4 v[184:187], v[50:51], off
	global_load_dwordx4 v[188:191], v[44:45], off
	global_load_dwordx4 v[192:195], v[40:41], off
	global_load_dwordx4 v[196:199], v[36:37], off
	s_waitcnt vmcnt(12)
	v_pk_mul_f32 v[200:201], v[72:73], v[72:73]
	v_pk_fma_f32 v[200:201], v[74:75], v[74:75], v[200:201]
	v_pk_fma_f32 v[200:201], v[76:77], v[76:77], v[200:201]
	v_pk_fma_f32 v[200:201], v[78:79], v[78:79], v[200:201]
	v_pk_fma_f32 v[200:201], v[80:81], v[80:81], v[200:201]
	v_pk_fma_f32 v[200:201], v[82:83], v[82:83], v[200:201]
	v_pk_fma_f32 v[200:201], v[84:85], v[84:85], v[200:201]
	v_pk_fma_f32 v[200:201], v[86:87], v[86:87], v[200:201]
	v_pk_mul_f32 v[202:203], v[88:89], v[88:89]
	v_pk_fma_f32 v[202:203], v[90:91], v[90:91], v[202:203]
	v_pk_fma_f32 v[202:203], v[92:93], v[92:93], v[202:203]
	v_pk_fma_f32 v[202:203], v[94:95], v[94:95], v[202:203]
	v_pk_fma_f32 v[202:203], v[96:97], v[96:97], v[202:203]
	v_pk_fma_f32 v[202:203], v[98:99], v[98:99], v[202:203]
	v_pk_fma_f32 v[202:203], v[100:101], v[100:101], v[202:203]
	v_pk_fma_f32 v[202:203], v[102:103], v[102:103], v[202:203]
	v_add_f32_e32 v200, v200, v201
	v_add_f32_e32 v202, v202, v203
	s_nop 0
	v_add_f32_dpp v200, v200, v200 quad_perm:[1,0,3,2] row_mask:0xf bank_mask:0xf bound_ctrl:1
	v_add_f32_dpp v202, v202, v202 quad_perm:[1,0,3,2] row_mask:0xf bank_mask:0xf bound_ctrl:1
	s_nop 0
	v_add_f32_dpp v200, v200, v200 quad_perm:[2,3,0,1] row_mask:0xf bank_mask:0xf bound_ctrl:1
	v_add_f32_dpp v202, v202, v202 quad_perm:[2,3,0,1] row_mask:0xf bank_mask:0xf bound_ctrl:1
	s_nop 0
	v_add_f32_dpp v200, v200, v200 row_half_mirror row_mask:0xf bank_mask:0xf bound_ctrl:1
	v_add_f32_dpp v202, v202, v202 row_half_mirror row_mask:0xf bank_mask:0xf bound_ctrl:1
	s_nop 0
	v_add_f32_dpp v200, v200, v200 row_mirror row_mask:0xf bank_mask:0xf bound_ctrl:1
	v_add_f32_dpp v202, v202, v202 row_mirror row_mask:0xf bank_mask:0xf bound_ctrl:1
	s_nop 0
	v_add_f32_dpp v200, v200, v200 row_bcast:15 row_mask:0xa bank_mask:0xf
	v_add_f32_dpp v202, v202, v202 row_bcast:15 row_mask:0xa bank_mask:0xf
	s_nop 0
	v_add_f32_dpp v200, v200, v200 row_bcast:31 row_mask:0xc bank_mask:0xf
	v_add_f32_dpp v202, v202, v202 row_bcast:31 row_mask:0xc bank_mask:0xf
	s_nop 0
	s_nop 1
	v_readlane_b32 s5, v200, 63
	v_readlane_b32 s6, v202, 63
	v_mov_b32_e32 v204, s5
	v_mov_b32_e32 v168, s6
	v_fma_f32 v204, v204, s10, v132
	v_fma_f32 v168, v168, s10, v132
	v_rsq_f32_e32 v204, v204
	v_rsq_f32_e32 v168, v168
	s_nop 0
	v_mov_b32_e32 v205, v204
	v_mov_b32_e32 v169, v168
	s_waitcnt vmcnt(0)
	v_pk_add_f32 v[184:185], v[184:185], 1.0 op_sel_hi:[1,0]
	v_pk_add_f32 v[186:187], v[186:187], 1.0 op_sel_hi:[1,0]
	v_pk_add_f32 v[188:189], v[188:189], 1.0 op_sel_hi:[1,0]
	v_pk_add_f32 v[190:191], v[190:191], 1.0 op_sel_hi:[1,0]
	v_pk_add_f32 v[192:193], v[192:193], 1.0 op_sel_hi:[1,0]
	v_pk_add_f32 v[194:195], v[194:195], 1.0 op_sel_hi:[1,0]
	v_pk_add_f32 v[196:197], v[196:197], 1.0 op_sel_hi:[1,0]
	v_pk_add_f32 v[198:199], v[198:199], 1.0 op_sel_hi:[1,0]
	v_pk_mul_f32 v[72:73], v[72:73], v[204:205]
	v_pk_mul_f32 v[72:73], v[136:137], v[72:73]
	v_pk_fma_f32 v[72:73], v[184:185], v[72:73], v[152:153]
	v_pk_mul_f32 v[74:75], v[74:75], v[204:205]
	v_pk_mul_f32 v[74:75], v[138:139], v[74:75]
	v_pk_fma_f32 v[74:75], v[186:187], v[74:75], v[154:155]
	v_cvt_pk_bf16_f32 v72, v72, v73
	v_cvt_pk_bf16_f32 v73, v74, v75
	global_store_dwordx2 v[56:57], v[72:73], off
	v_pk_mul_f32 v[76:77], v[76:77], v[204:205]
	v_pk_mul_f32 v[76:77], v[140:141], v[76:77]
	v_pk_fma_f32 v[76:77], v[188:189], v[76:77], v[156:157]
	v_pk_mul_f32 v[78:79], v[78:79], v[204:205]
	v_pk_mul_f32 v[78:79], v[142:143], v[78:79]
	v_pk_fma_f32 v[78:79], v[190:191], v[78:79], v[158:159]
	v_cvt_pk_bf16_f32 v76, v76, v77
	v_cvt_pk_bf16_f32 v77, v78, v79
	global_store_dwordx2 v[56:57], v[76:77], off offset:512
	v_pk_mul_f32 v[80:81], v[80:81], v[204:205]
	v_pk_mul_f32 v[80:81], v[144:145], v[80:81]
	v_pk_fma_f32 v[80:81], v[192:193], v[80:81], v[160:161]
	v_pk_mul_f32 v[82:83], v[82:83], v[204:205]
	v_pk_mul_f32 v[82:83], v[146:147], v[82:83]
	v_pk_fma_f32 v[82:83], v[194:195], v[82:83], v[162:163]
	v_cvt_pk_bf16_f32 v80, v80, v81
	v_cvt_pk_bf16_f32 v81, v82, v83
	global_store_dwordx2 v[56:57], v[80:81], off offset:1024
	v_pk_mul_f32 v[84:85], v[84:85], v[204:205]
	v_pk_mul_f32 v[84:85], v[148:149], v[84:85]
	v_pk_fma_f32 v[84:85], v[196:197], v[84:85], v[164:165]
	v_pk_mul_f32 v[86:87], v[86:87], v[204:205]
	v_pk_mul_f32 v[86:87], v[150:151], v[86:87]
	v_pk_fma_f32 v[86:87], v[198:199], v[86:87], v[166:167]
	v_cvt_pk_bf16_f32 v84, v84, v85
	v_cvt_pk_bf16_f32 v85, v86, v87
	global_store_dwordx2 v[56:57], v[84:85], off offset:1536
	v_pk_mul_f32 v[88:89], v[88:89], v[168:169]
	v_pk_mul_f32 v[88:89], v[136:137], v[88:89]
	v_pk_fma_f32 v[88:89], v[184:185], v[88:89], v[152:153]
	v_pk_mul_f32 v[90:91], v[90:91], v[168:169]
	v_pk_mul_f32 v[90:91], v[138:139], v[90:91]
	v_pk_fma_f32 v[90:91], v[186:187], v[90:91], v[154:155]
	v_cvt_pk_bf16_f32 v88, v88, v89
	v_cvt_pk_bf16_f32 v89, v90, v91
	global_store_dwordx2 v[56:57], v[88:89], off offset:2048
	v_pk_mul_f32 v[92:93], v[92:93], v[168:169]
	v_pk_mul_f32 v[92:93], v[140:141], v[92:93]
	v_pk_fma_f32 v[92:93], v[188:189], v[92:93], v[156:157]
	v_pk_mul_f32 v[94:95], v[94:95], v[168:169]
	v_pk_mul_f32 v[94:95], v[142:143], v[94:95]
	v_pk_fma_f32 v[94:95], v[190:191], v[94:95], v[158:159]
	v_cvt_pk_bf16_f32 v92, v92, v93
	v_cvt_pk_bf16_f32 v93, v94, v95
	global_store_dwordx2 v[56:57], v[92:93], off offset:2560
	v_pk_mul_f32 v[96:97], v[96:97], v[168:169]
	v_pk_mul_f32 v[96:97], v[144:145], v[96:97]
	v_pk_fma_f32 v[96:97], v[192:193], v[96:97], v[160:161]
	v_pk_mul_f32 v[98:99], v[98:99], v[168:169]
	v_pk_mul_f32 v[98:99], v[146:147], v[98:99]
	v_pk_fma_f32 v[98:99], v[194:195], v[98:99], v[162:163]
	v_cvt_pk_bf16_f32 v96, v96, v97
	v_cvt_pk_bf16_f32 v97, v98, v99
	global_store_dwordx2 v[56:57], v[96:97], off offset:3072
	v_pk_mul_f32 v[100:101], v[100:101], v[168:169]
	v_pk_mul_f32 v[100:101], v[148:149], v[100:101]
	v_pk_fma_f32 v[100:101], v[196:197], v[100:101], v[164:165]
	v_pk_mul_f32 v[102:103], v[102:103], v[168:169]
	v_pk_mul_f32 v[102:103], v[150:151], v[102:103]
	v_pk_fma_f32 v[102:103], v[198:199], v[102:103], v[166:167]
	v_cvt_pk_bf16_f32 v100, v100, v101
	v_cvt_pk_bf16_f32 v101, v102, v103
	global_store_dwordx2 v[56:57], v[100:101], off offset:3584
	s_cmp_lt_i32 s4, s2
	s_cbranch_scc1 .LBB0_1242
	v_readlane_b32 s42, v208, 51
	v_readlane_b32 s54, v209, 14
	v_readlane_b32 s43, v208, 52
	v_readlane_b32 s55, v209, 15
	s_mov_b32 s56, 0x10000
	s_mov_b32 s57, 0x20000
	s_mov_b32 s58, 0x30000
	s_movk_i32 s59, 0x70
	s_movk_i32 s53, 0x2000
	s_mov_b32 s52, 0xb000
